# v109 + static first work-queue index (first unit = blockIdx.x without an atomic; dynamic pops offset by gridDim)
# speedup vs baseline: 1.0025x; 1.0025x over previous
; #define LAS __attribute__((address_space(3)))
; __global__ void __launch_bounds__(NWAVES * 64, 2) hymba_fwd(Args args) {
;     ...
;         for (int it = 0;; ++it) {
;             if (it == 0) __syncthreads();
;             volatile LAS int* slot = (volatile LAS int*)(F.lds + MISC_OFF) + 16 + (it & 1);
;             if (threadIdx.x == 0) *slot = (int)__hip_atomic_fetch_add((unsigned*)(CTL_ + CW_QUEUE + 64 * (l + 4 * rep)), 1u, __ATOMIC_RELAXED, __HIP_MEMORY_SCOPE_AGENT);
;             __syncthreads();
;             const int idx = __builtin_amdgcn_readfirstlane(*slot);
;             if (idx >= 128 + 512 + NCHUNK * 4) break;
.LBB0_470:
	s_and_b32 s0, s52, 1
	s_lshl_b32 s0, s0, 2
	s_add_i32 s10, s0, 0
	s_add_i32 s10, s10, 0x20180
	s_and_saveexec_b64 s[0:1], s[38:39]
	s_cbranch_execz .LBB0_474
	v_mov_b32_e32 v3, 0x20258
	s_mov_b64 s[6:7], exec
	v_add_u32_e32 v3, 0, v3
	ds_read_b32 v4, v3
	ds_read_b32 v3, v3 offset:4
	s_waitcnt lgkmcnt(1)
	v_readfirstlane_b32 s11, v4
	s_waitcnt lgkmcnt(0)
	v_readfirstlane_b32 s12, v3
	v_mbcnt_lo_u32_b32 v3, s6, 0
	v_mbcnt_hi_u32_b32 v3, s7, v3
	v_cmp_eq_u32_e32 vcc, 0, v3
	s_and_saveexec_b64 s[8:9], vcc
	s_cbranch_execz .LBB0_473
	s_lshl_b64 s[14:15], s[4:5], 2
	s_add_u32 s14, s11, s14
	s_addc_u32 s15, s12, s15
	s_bcnt1_i32_b64 s6, s[6:7]
	v_mov_b32_e32 v4, s6
	s_cmp_eq_u32 s52, 0
	s_cbranch_scc1 .Lq_first
	s_cmp_lg_u32 s98, 0
	s_cbranch_scc1 .Lq_have
	global_atomic_add v238, v234, v4, s[14:15] sc0
.Lq_have:
	s_mov_b32 s98, 0
	s_waitcnt vmcnt(0)
	v_add_u32_e32 v5, s33, v238
	s_branch .Lq_done
.Lq_first:
	v_mov_b32_e32 v5, s2
.Lq_done:
.LBB0_473:
	s_or_b64 exec, exec, s[8:9]
	v_readfirstlane_b32 s6, v5
	v_mov_b32_e32 v4, s10
	s_nop 0
	v_add_u32_e32 v3, s6, v3
	ds_write_b32 v4, v3
